# mixer C: hand-scheduled inb apply block (4 VALU per element), QK negm passed as C operand (no copies), max3 nops stripped, PV prefetch
# speedup vs baseline: 1.0052x; 1.0052x over previous
; #define LAS __attribute__((address_space(3)))
;     __device__ __forceinline__ void apply(f32x16& p0, f32x16& p1, int, int) const {
;         if (inb) {
; #pragma unroll
;             for (int r = 0; r < 16; ++r) { const float cr = (float)((r & 3) + 8 * (r >> 2));
;                 { const float d = __builtin_fmaf(-cr, strf, af); const float v = __builtin_fmaf(-slope2, __builtin_fabsf(d), p0[r]); p0[r] = (__builtin_fabsf(d) <= limf) ? v : -INFINITY; }
;                 { const float d = __builtin_fmaf(-(cr + 32.f), strf, af); const float v = __builtin_fmaf(-slope2, __builtin_fabsf(d), p1[r]); p1[r] = (__builtin_fabsf(d) <= limf) ? v : -INFINITY; } }
;         } else {
; #pragma unroll
;             for (int r = 0; r < 16; ++r) { const float cr = (float)((r & 3) + 8 * (r >> 2));
;                 { const float d = __builtin_fmaf(-cr, strf, af); const float v = __builtin_fmaf(-slope2, __builtin_fabsf(d), p0[r]); p0[r] = ((__builtin_fabsf(d) <= limf) && (d <= tqf) && (d > tqmS)) ? v : -INFINITY; }
;                 { const float d = __builtin_fmaf(-(cr + 32.f), strf, af); const float v = __builtin_fmaf(-slope2, __builtin_fabsf(d), p1[r]); p1[r] = ((__builtin_fabsf(d) <= limf) && (d <= tqf) && (d > tqmS)) ? v : -INFINITY; } }
;         }
; __device__ __forceinline__ void qkt2(f32x16& p0, f32x16& p1, LAS const unsigned char* kslot, const bf16x8 (&qr)[4], const f32x16& negm, int r32, int hi) {
; #pragma unroll
;     for (int d0 = 0; d0 < 4; ++d0) {
;         LAS const unsigned char* kb = kslot + (2 * d0 + hi) * 1024 + ((r32 ^ (2 * d0 + hi)) * 16); asm volatile("" : "+v"(kb));
;         const bf16x8 b0 = *(LAS const bf16x8*)(kb);
;         const bf16x8 b1 = *(LAS const bf16x8*)(kb + 512);
;         if (d0 == 0) { p0 = __builtin_amdgcn_mfma_f32_32x32x16_bf16(b0, qr[0], negm, 0, 0, 0); p1 = __builtin_amdgcn_mfma_f32_32x32x16_bf16(b1, qr[0], negm, 0, 0, 0); }
;         else { p0 = __builtin_amdgcn_mfma_f32_32x32x16_bf16(b0, qr[d0], p0, 0, 0, 0); p1 = __builtin_amdgcn_mfma_f32_32x32x16_bf16(b1, qr[d0], p1, 0, 0, 0); }
;     }
; }
.LBB0_40:
	v_lshlrev_b32_e32 v50, s43, v236
	v_subrev_u32_e32 v50, s42, v50
	v_add_u32_e32 v50, v50, v188
	v_cvt_f32_i32_e32 v218, v50
	v_mov_b32_e32 v50, v237
	ds_read_b128 v[176:179], v50 offset:512
	ds_read_b128 v[66:69], v50
	v_mov_b32_e32 v169, v238
	s_lshl_b32 s2, 1, s43
	s_waitcnt lgkmcnt(0)
	v_mfma_f32_32x32x16_bf16 v[50:65], v[66:69], v[82:85], v[34:49]
	v_cvt_f32_u32_e32 v220, s2
	s_lshl_b32 s2, 64, s43
	v_mfma_f32_32x32x16_bf16 v[66:81], v[176:179], v[82:85], v[34:49]
	ds_read_b128 v[176:179], v169 offset:512
	ds_read_b128 v[180:183], v169
	v_mov_b32_e32 v169, v239
	s_cmp_gt_i32 s42, -1
	v_cvt_f32_u32_e32 v171, s2
	s_cselect_b64 s[2:3], -1, 0
	s_lshl_b32 s10, 63, s43
	s_waitcnt lgkmcnt(0)
	v_mfma_f32_32x32x16_bf16 v[50:65], v[180:183], v[86:89], v[50:65]
	s_add_i32 s10, s42, s10
	s_cmp_lt_i32 s10, s23
	s_cselect_b64 s[10:11], -1, 0
	s_and_b64 s[10:11], s[2:3], s[10:11]
	v_sub_f32_e32 v248, v218, v220
	v_cmp_le_f32_e64 s[42:43], |v218|, v171
	s_mov_b64 s[2:3], -1
	v_mfma_f32_32x32x16_bf16 v[66:81], v[176:179], v[86:89], v[66:81]
	ds_read_b128 v[176:179], v169 offset:512
	ds_read_b128 v[180:183], v169
	v_mov_b32_e32 v169, v240
	s_and_b64 vcc, exec, s[10:11]
	v_cmp_le_f32_e64 s[10:11], |v248|, v171
	v_fma_f32 v249, -2.0, v220, v218
	v_fmamk_f32 v247, v220, 0xc2680000, v218
	s_waitcnt lgkmcnt(0)
	v_mfma_f32_32x32x16_bf16 v[50:65], v[180:183], v[90:93], v[50:65]
	v_fmamk_f32 v246, v220, 0xc1d80000, v218
	v_fmamk_f32 v245, v220, 0xc26c0000, v218
	v_mfma_f32_32x32x16_bf16 v[66:81], v[176:179], v[90:93], v[66:81]
	ds_read_b128 v[176:179], v169 offset:512
	ds_read_b128 v[180:183], v169
	s_waitcnt lgkmcnt(0)
	v_mfma_f32_32x32x16_bf16 v[50:65], v[180:183], v[94:97], v[50:65]
	v_mfma_f32_32x32x16_bf16 v[66:81], v[176:179], v[94:97], v[66:81]
	s_nop 10
	v_fma_f32 v250, v186, |v218|, v50
	s_cbranch_vccnz .LBB0_42
	v_cvt_f32_i32_e32 v176, v188
	v_subrev_u32_e32 v50, s23, v188
	v_cvt_f32_i32_e32 v177, v50
	v_fmamk_f32 v50, v220, 0xc2000000, v218
	v_cmp_le_f32_e32 vcc, v218, v176
	s_and_b64 s[2:3], s[42:43], vcc
	v_cmp_gt_f32_e32 vcc, v218, v177
	s_and_b64 vcc, s[2:3], vcc
	v_cmp_le_f32_e64 s[2:3], |v50|, v171
	v_cndmask_b32_e32 v188, v226, v250, vcc
	v_cmp_le_f32_e32 vcc, v50, v176
	s_and_b64 s[2:3], s[2:3], vcc
	v_cmp_gt_f32_e32 vcc, v50, v177
	v_fma_f32 v169, v186, |v50|, v66
	s_and_b64 vcc, s[2:3], vcc
	v_cndmask_b32_e32 v50, v226, v169, vcc
	v_cmp_le_f32_e32 vcc, v248, v176
	s_and_b64 s[2:3], s[10:11], vcc
	v_cmp_gt_f32_e32 vcc, v248, v177
	v_fma_f32 v169, v186, |v248|, v51
	s_and_b64 vcc, s[2:3], vcc
	v_cndmask_b32_e32 v189, v226, v169, vcc
	v_fmamk_f32 v169, v220, 0xc2040000, v218
	v_cmp_le_f32_e64 s[2:3], |v169|, v171
	v_cmp_le_f32_e32 vcc, v169, v176
	s_and_b64 s[2:3], s[2:3], vcc
	v_cmp_gt_f32_e32 vcc, v169, v177
	v_fma_f32 v178, v186, |v169|, v67
	s_and_b64 vcc, s[2:3], vcc
	v_cndmask_b32_e32 v169, v226, v178, vcc
	v_cmp_le_f32_e64 s[2:3], |v249|, v171
	v_cmp_le_f32_e32 vcc, v249, v176
	s_and_b64 s[2:3], s[2:3], vcc
	v_cmp_gt_f32_e32 vcc, v249, v177
	v_fma_f32 v178, v186, |v249|, v52
	s_and_b64 vcc, s[2:3], vcc
	v_cndmask_b32_e32 v190, v226, v178, vcc
	v_fmamk_f32 v178, v220, 0xc2080000, v218
	v_cmp_le_f32_e64 s[2:3], |v178|, v171
	v_cmp_le_f32_e32 vcc, v178, v176
	s_and_b64 s[2:3], s[2:3], vcc
	v_cmp_gt_f32_e32 vcc, v178, v177
	v_fma_f32 v179, v186, |v178|, v68
	s_and_b64 vcc, s[2:3], vcc
	v_fmamk_f32 v178, v220, 0xc0400000, v218
	v_cndmask_b32_e32 v194, v226, v179, vcc
	v_cmp_le_f32_e64 s[2:3], |v178|, v171
	v_cmp_le_f32_e32 vcc, v178, v176
	s_and_b64 s[2:3], s[2:3], vcc
	v_cmp_gt_f32_e32 vcc, v178, v177
	v_fma_f32 v179, v186, |v178|, v53
	s_and_b64 vcc, s[2:3], vcc
	v_fmamk_f32 v178, v220, 0xc20c0000, v218
	v_cndmask_b32_e32 v191, v226, v179, vcc
	v_cmp_le_f32_e64 s[2:3], |v178|, v171
	v_cmp_le_f32_e32 vcc, v178, v176
	s_and_b64 s[2:3], s[2:3], vcc
	v_cmp_gt_f32_e32 vcc, v178, v177
	v_fma_f32 v179, v186, |v178|, v69
	s_and_b64 vcc, s[2:3], vcc
	v_fmamk_f32 v178, v220, 0xc1000000, v218
	v_cndmask_b32_e32 v195, v226, v179, vcc
	v_cmp_le_f32_e64 s[2:3], |v178|, v171
	v_cmp_le_f32_e32 vcc, v178, v176
	s_and_b64 s[2:3], s[2:3], vcc
	v_cmp_gt_f32_e32 vcc, v178, v177
	v_fma_f32 v179, v186, |v178|, v54
	s_and_b64 vcc, s[2:3], vcc
	v_fmamk_f32 v178, v220, 0xc2200000, v218
	v_cndmask_b32_e32 v192, v226, v179, vcc
	v_cmp_le_f32_e64 s[2:3], |v178|, v171
	v_cmp_le_f32_e32 vcc, v178, v176
	s_and_b64 s[2:3], s[2:3], vcc
	v_cmp_gt_f32_e32 vcc, v178, v177
	v_fma_f32 v179, v186, |v178|, v70
	s_and_b64 vcc, s[2:3], vcc
	v_fmamk_f32 v178, v220, 0xc1100000, v218
	v_cndmask_b32_e32 v196, v226, v179, vcc
	v_cmp_le_f32_e64 s[2:3], |v178|, v171
	v_cmp_le_f32_e32 vcc, v178, v176
	s_and_b64 s[2:3], s[2:3], vcc
	v_cmp_gt_f32_e32 vcc, v178, v177
	v_fma_f32 v179, v186, |v178|, v55
	s_and_b64 vcc, s[2:3], vcc
	v_fmamk_f32 v178, v220, 0xc2240000, v218
	v_cndmask_b32_e32 v193, v226, v179, vcc
	v_cmp_le_f32_e64 s[2:3], |v178|, v171
	v_cmp_le_f32_e32 vcc, v178, v176
	s_and_b64 s[2:3], s[2:3], vcc
	v_cmp_gt_f32_e32 vcc, v178, v177
	v_fma_f32 v179, v186, |v178|, v71
	s_and_b64 vcc, s[2:3], vcc
	v_fmamk_f32 v178, v220, 0xc1200000, v218
	v_cndmask_b32_e32 v197, v226, v179, vcc
	v_cmp_le_f32_e64 s[2:3], |v178|, v171
	v_cmp_le_f32_e32 vcc, v178, v176
	s_and_b64 s[2:3], s[2:3], vcc
	v_cmp_gt_f32_e32 vcc, v178, v177
	v_fma_f32 v179, v186, |v178|, v56
	s_and_b64 vcc, s[2:3], vcc
	v_fmamk_f32 v178, v220, 0xc2280000, v218
	v_cndmask_b32_e32 v198, v226, v179, vcc
	v_cmp_le_f32_e64 s[2:3], |v178|, v171
	v_cmp_le_f32_e32 vcc, v178, v176
	s_and_b64 s[2:3], s[2:3], vcc
	v_cmp_gt_f32_e32 vcc, v178, v177
	v_fma_f32 v179, v186, |v178|, v72
	s_and_b64 vcc, s[2:3], vcc
;     __device__ __forceinline__ void apply(f32x16& p0, f32x16& p1, int, int) const {
;     ...
;             for (int r = 0; r < 16; ++r) { const float cr = (float)((r & 3) + 8 * (r >> 2));
;                 { const float d = __builtin_fmaf(-cr, strf, af); const float v = __builtin_fmaf(-slope2, __builtin_fabsf(d), p0[r]); p0[r] = ((__builtin_fabsf(d) <= limf) && (d <= tqf) && (d > tqmS)) ? v : -INFINITY; }
;                 { const float d = __builtin_fmaf(-(cr + 32.f), strf, af); const float v = __builtin_fmaf(-slope2, __builtin_fabsf(d), p1[r]); p1[r] = ((__builtin_fabsf(d) <= limf) && (d <= tqf) && (d > tqmS)) ? v : -INFINITY; } }
	v_fmamk_f32 v178, v220, 0xc1300000, v218
	v_cndmask_b32_e32 v200, v226, v179, vcc
	v_cmp_le_f32_e64 s[2:3], |v178|, v171
	v_cmp_le_f32_e32 vcc, v178, v176
	s_and_b64 s[2:3], s[2:3], vcc
	v_cmp_gt_f32_e32 vcc, v178, v177
	v_fma_f32 v179, v186, |v178|, v57
	s_and_b64 vcc, s[2:3], vcc
	v_fmamk_f32 v178, v220, 0xc22c0000, v218
	v_cndmask_b32_e32 v199, v226, v179, vcc
	v_cmp_le_f32_e64 s[2:3], |v178|, v171
	v_cmp_le_f32_e32 vcc, v178, v176
	s_and_b64 s[2:3], s[2:3], vcc
	v_cmp_gt_f32_e32 vcc, v178, v177
	v_fma_f32 v179, v186, |v178|, v73
	s_and_b64 vcc, s[2:3], vcc
	v_fmamk_f32 v178, v220, 0xc1800000, v218
	v_cndmask_b32_e32 v201, v226, v179, vcc
	v_cmp_le_f32_e64 s[2:3], |v178|, v171
	v_cmp_le_f32_e32 vcc, v178, v176
	s_and_b64 s[2:3], s[2:3], vcc
	v_cmp_gt_f32_e32 vcc, v178, v177
	v_fma_f32 v179, v186, |v178|, v58
	s_and_b64 vcc, s[2:3], vcc
	v_fmamk_f32 v178, v220, 0xc2400000, v218
	v_cndmask_b32_e32 v202, v226, v179, vcc
	v_cmp_le_f32_e64 s[2:3], |v178|, v171
	v_cmp_le_f32_e32 vcc, v178, v176
	s_and_b64 s[2:3], s[2:3], vcc
	v_cmp_gt_f32_e32 vcc, v178, v177
	v_fma_f32 v179, v186, |v178|, v74
	s_and_b64 vcc, s[2:3], vcc
	v_fmamk_f32 v178, v220, 0xc1880000, v218
	v_cndmask_b32_e32 v204, v226, v179, vcc
	v_cmp_le_f32_e64 s[2:3], |v178|, v171
	v_cmp_le_f32_e32 vcc, v178, v176
	s_and_b64 s[2:3], s[2:3], vcc
	v_cmp_gt_f32_e32 vcc, v178, v177
	v_fma_f32 v179, v186, |v178|, v59
	s_and_b64 vcc, s[2:3], vcc
	v_fmamk_f32 v178, v220, 0xc2440000, v218
	v_cndmask_b32_e32 v203, v226, v179, vcc
	v_cmp_le_f32_e64 s[2:3], |v178|, v171
	v_cmp_le_f32_e32 vcc, v178, v176
	s_and_b64 s[2:3], s[2:3], vcc
	v_cmp_gt_f32_e32 vcc, v178, v177
	v_fma_f32 v179, v186, |v178|, v75
	s_and_b64 vcc, s[2:3], vcc
	v_fmamk_f32 v178, v220, 0xc1900000, v218
	v_cndmask_b32_e32 v205, v226, v179, vcc
	v_cmp_le_f32_e64 s[2:3], |v178|, v171
	v_cmp_le_f32_e32 vcc, v178, v176
	s_and_b64 s[2:3], s[2:3], vcc
	v_cmp_gt_f32_e32 vcc, v178, v177
	v_fma_f32 v179, v186, |v178|, v60
	s_and_b64 vcc, s[2:3], vcc
	v_fmamk_f32 v178, v220, 0xc2480000, v218
	v_cndmask_b32_e32 v206, v226, v179, vcc
	v_cmp_le_f32_e64 s[2:3], |v178|, v171
	v_cmp_le_f32_e32 vcc, v178, v176
	s_and_b64 s[2:3], s[2:3], vcc
	v_cmp_gt_f32_e32 vcc, v178, v177
	v_fma_f32 v179, v186, |v178|, v76
	s_and_b64 vcc, s[2:3], vcc
	v_fmamk_f32 v178, v220, 0xc1980000, v218
	v_cndmask_b32_e32 v208, v226, v179, vcc
	v_cmp_le_f32_e64 s[2:3], |v178|, v171
	v_cmp_le_f32_e32 vcc, v178, v176
	s_and_b64 s[2:3], s[2:3], vcc
	v_cmp_gt_f32_e32 vcc, v178, v177
	v_fma_f32 v179, v186, |v178|, v61
	s_and_b64 vcc, s[2:3], vcc
	v_fmamk_f32 v178, v220, 0xc24c0000, v218
	v_cndmask_b32_e32 v207, v226, v179, vcc
	v_cmp_le_f32_e64 s[2:3], |v178|, v171
	v_cmp_le_f32_e32 vcc, v178, v176
	s_and_b64 s[2:3], s[2:3], vcc
	v_cmp_gt_f32_e32 vcc, v178, v177
	v_fma_f32 v179, v186, |v178|, v77
	s_and_b64 vcc, s[2:3], vcc
	v_fmamk_f32 v178, v220, 0xc1c00000, v218
	v_cndmask_b32_e32 v209, v226, v179, vcc
	v_cmp_le_f32_e64 s[2:3], |v178|, v171
	v_cmp_le_f32_e32 vcc, v178, v176
	s_and_b64 s[2:3], s[2:3], vcc
	v_cmp_gt_f32_e32 vcc, v178, v177
	v_fma_f32 v179, v186, |v178|, v62
	s_and_b64 vcc, s[2:3], vcc
	v_fmamk_f32 v178, v220, 0xc2600000, v218
	v_cndmask_b32_e32 v210, v226, v179, vcc
	v_cmp_le_f32_e64 s[2:3], |v178|, v171
	v_cmp_le_f32_e32 vcc, v178, v176
	s_and_b64 s[2:3], s[2:3], vcc
	v_cmp_gt_f32_e32 vcc, v178, v177
	v_fma_f32 v179, v186, |v178|, v78
	s_and_b64 vcc, s[2:3], vcc
	v_fmamk_f32 v178, v220, 0xc1c80000, v218
	v_cndmask_b32_e32 v212, v226, v179, vcc
	v_cmp_le_f32_e64 s[2:3], |v178|, v171
	v_cmp_le_f32_e32 vcc, v178, v176
	s_and_b64 s[2:3], s[2:3], vcc
	v_cmp_gt_f32_e32 vcc, v178, v177
	v_fma_f32 v179, v186, |v178|, v63
	s_and_b64 vcc, s[2:3], vcc
	v_fmamk_f32 v178, v220, 0xc2640000, v218
	v_cndmask_b32_e32 v211, v226, v179, vcc
	v_cmp_le_f32_e64 s[2:3], |v178|, v171
	v_cmp_le_f32_e32 vcc, v178, v176
	s_and_b64 s[2:3], s[2:3], vcc
	v_cmp_gt_f32_e32 vcc, v178, v177
	v_fma_f32 v179, v186, |v178|, v79
	s_and_b64 vcc, s[2:3], vcc
	v_fmamk_f32 v178, v220, 0xc1d00000, v218
	v_cndmask_b32_e32 v213, v226, v179, vcc
	v_cmp_le_f32_e64 s[2:3], |v178|, v171
	v_cmp_le_f32_e32 vcc, v178, v176
	s_and_b64 s[2:3], s[2:3], vcc
	v_cmp_gt_f32_e32 vcc, v178, v177
	v_fma_f32 v179, v186, |v178|, v64
	s_and_b64 vcc, s[2:3], vcc
	v_cndmask_b32_e32 v214, v226, v179, vcc
	v_cmp_le_f32_e64 s[2:3], |v247|, v171
	v_cmp_le_f32_e32 vcc, v247, v176
	s_and_b64 s[2:3], s[2:3], vcc
	v_cmp_gt_f32_e32 vcc, v247, v177
	v_fma_f32 v178, v186, |v247|, v80
	s_and_b64 vcc, s[2:3], vcc
	v_cndmask_b32_e32 v216, v226, v178, vcc
	v_cmp_le_f32_e64 s[2:3], |v246|, v171
	v_cmp_le_f32_e32 vcc, v246, v176
	s_and_b64 s[2:3], s[2:3], vcc
	v_cmp_gt_f32_e32 vcc, v246, v177
	v_fma_f32 v178, v186, |v246|, v65
	s_and_b64 vcc, s[2:3], vcc
	v_cndmask_b32_e32 v215, v226, v178, vcc
	v_cmp_le_f32_e64 s[2:3], |v245|, v171
	v_cmp_le_f32_e32 vcc, v245, v176
	s_and_b64 s[2:3], s[2:3], vcc
	v_cmp_gt_f32_e32 vcc, v245, v177
	v_fma_f32 v178, v186, |v245|, v81
	s_and_b64 vcc, s[2:3], vcc
	v_cndmask_b32_e32 v217, v226, v178, vcc
	s_mov_b64 s[2:3], 0
; __device__ __forceinline__ float max3f(float a, float b, float c) { float r; asm("v_max3_f32 %0, %1, %2, %3" : "=v"(r) : "v"(a), "v"(b), "v"(c)); return r; }
;     __device__ __forceinline__ void apply(f32x16& p0, f32x16& p1, int, int) const {
;         if (inb) {
; #pragma unroll
;             for (int r = 0; r < 16; ++r) { const float cr = (float)((r & 3) + 8 * (r >> 2));
;                 { const float d = __builtin_fmaf(-cr, strf, af); const float v = __builtin_fmaf(-slope2, __builtin_fabsf(d), p0[r]); p0[r] = (__builtin_fabsf(d) <= limf) ? v : -INFINITY; }
;                 { const float d = __builtin_fmaf(-(cr + 32.f), strf, af); const float v = __builtin_fmaf(-slope2, __builtin_fabsf(d), p1[r]); p1[r] = (__builtin_fabsf(d) <= limf) ? v : -INFINITY; } }
; __device__ __forceinline__ float rowmax32(const f32x16& p0, const f32x16& p1) {
;     float a = max3f(p0[0], p0[1], p1[0]), b = max3f(p0[2], p0[3], p1[1]); a = max3f(a, p1[2], p1[3]);
; #pragma unroll
;     for (int r = 4; r < 16; r += 4) { a = max3f(a, p0[r], p0[r + 1]); b = max3f(b, p0[r + 2], p0[r + 3]); a = max3f(a, p1[r], p1[r + 1]); b = max3f(b, p1[r + 2], p1[r + 3]); }
;     return fmaxf(a, b);
; }
.LBB0_42:
	s_andn2_b64 vcc, exec, s[2:3]
	s_cbranch_vccnz .LBB0_44
	v_fma_f32 v179, s62, v220, v218
	v_fma_f32 v189, v186, |v248|, v51
	v_fma_f32 v190, v186, |v249|, v52
	v_fma_f32 v191, v186, |v179|, v53
	v_cmp_le_f32_e64 vcc, |v249|, v171
	v_cmp_le_f32_e64 s[2:3], |v179|, v171
	v_cndmask_b32_e64 v188, v226, v250, s[42:43]
	v_cndmask_b32_e64 v189, v226, v189, s[10:11]
	v_cndmask_b32_e32 v190, v226, v190, vcc
	v_cndmask_b32_e64 v191, v226, v191, s[2:3]
	v_fma_f32 v176, s63, v220, v218
	v_fma_f32 v177, s66, v220, v218
	v_fma_f32 v178, s67, v220, v218
	v_fma_f32 v179, s70, v220, v218
	v_fma_f32 v192, v186, |v176|, v54
	v_fma_f32 v193, v186, |v177|, v55
	v_fma_f32 v198, v186, |v178|, v56
	v_fma_f32 v199, v186, |v179|, v57
	v_cmp_le_f32_e64 vcc, |v176|, v171
	v_cmp_le_f32_e64 s[2:3], |v177|, v171
	v_cmp_le_f32_e64 s[10:11], |v178|, v171
	v_cmp_le_f32_e64 s[42:43], |v179|, v171
	v_cndmask_b32_e32 v192, v226, v192, vcc
	v_cndmask_b32_e64 v193, v226, v193, s[2:3]
	v_cndmask_b32_e64 v198, v226, v198, s[10:11]
	v_cndmask_b32_e64 v199, v226, v199, s[42:43]
	v_fma_f32 v176, s71, v220, v218
	v_fma_f32 v177, s74, v220, v218
	v_fma_f32 v178, s75, v220, v218
	v_fma_f32 v179, s78, v220, v218
	v_fma_f32 v202, v186, |v176|, v58
	v_fma_f32 v203, v186, |v177|, v59
	v_fma_f32 v206, v186, |v178|, v60
	v_fma_f32 v207, v186, |v179|, v61
	v_cmp_le_f32_e64 vcc, |v176|, v171
	v_cmp_le_f32_e64 s[2:3], |v177|, v171
	v_cmp_le_f32_e64 s[10:11], |v178|, v171
	v_cmp_le_f32_e64 s[42:43], |v179|, v171
	v_cndmask_b32_e32 v202, v226, v202, vcc
	v_cndmask_b32_e64 v203, v226, v203, s[2:3]
	v_cndmask_b32_e64 v206, v226, v206, s[10:11]
	v_cndmask_b32_e64 v207, v226, v207, s[42:43]
	v_fma_f32 v176, s79, v220, v218
	v_fma_f32 v177, s82, v220, v218
	v_fma_f32 v178, s83, v220, v218
	v_fma_f32 v210, v186, |v176|, v62
	v_fma_f32 v211, v186, |v177|, v63
	v_fma_f32 v214, v186, |v178|, v64
	v_fma_f32 v215, v186, |v246|, v65
	v_cmp_le_f32_e64 vcc, |v176|, v171
	v_cmp_le_f32_e64 s[2:3], |v177|, v171
	v_cmp_le_f32_e64 s[10:11], |v178|, v171
	v_cmp_le_f32_e64 s[42:43], |v246|, v171
	v_cndmask_b32_e32 v210, v226, v210, vcc
	v_cndmask_b32_e64 v211, v226, v211, s[2:3]
	v_cndmask_b32_e64 v214, v226, v214, s[10:11]
	v_cndmask_b32_e64 v215, v226, v215, s[42:43]
	v_fma_f32 v176, s58, v220, v218
	v_fma_f32 v177, s59, v220, v218
	v_fma_f32 v178, s60, v220, v218
	v_fma_f32 v179, s61, v220, v218
	v_fma_f32 v50, v186, |v176|, v66
	v_fma_f32 v169, v186, |v177|, v67
	v_fma_f32 v194, v186, |v178|, v68
	v_fma_f32 v195, v186, |v179|, v69
	v_cmp_le_f32_e64 vcc, |v176|, v171
	v_cmp_le_f32_e64 s[2:3], |v177|, v171
	v_cmp_le_f32_e64 s[10:11], |v178|, v171
	v_cmp_le_f32_e64 s[42:43], |v179|, v171
	v_cndmask_b32_e32 v50, v226, v50, vcc
	v_cndmask_b32_e64 v169, v226, v169, s[2:3]
	v_cndmask_b32_e64 v194, v226, v194, s[10:11]
	v_cndmask_b32_e64 v195, v226, v195, s[42:43]
	v_fma_f32 v176, s64, v220, v218
	v_fma_f32 v177, s65, v220, v218
	v_fma_f32 v178, s68, v220, v218
	v_fma_f32 v179, s69, v220, v218
	v_fma_f32 v196, v186, |v176|, v70
	v_fma_f32 v197, v186, |v177|, v71
	v_fma_f32 v200, v186, |v178|, v72
	v_fma_f32 v201, v186, |v179|, v73
	v_cmp_le_f32_e64 vcc, |v176|, v171
	v_cmp_le_f32_e64 s[2:3], |v177|, v171
	v_cmp_le_f32_e64 s[10:11], |v178|, v171
	v_cmp_le_f32_e64 s[42:43], |v179|, v171
	v_cndmask_b32_e32 v196, v226, v196, vcc
	v_cndmask_b32_e64 v197, v226, v197, s[2:3]
	v_cndmask_b32_e64 v200, v226, v200, s[10:11]
	v_cndmask_b32_e64 v201, v226, v201, s[42:43]
	v_fma_f32 v176, s72, v220, v218
	v_fma_f32 v177, s73, v220, v218
	v_fma_f32 v178, s76, v220, v218
	v_fma_f32 v179, s77, v220, v218
	v_fma_f32 v204, v186, |v176|, v74
	v_fma_f32 v205, v186, |v177|, v75
	v_fma_f32 v208, v186, |v178|, v76
	v_fma_f32 v209, v186, |v179|, v77
	v_cmp_le_f32_e64 vcc, |v176|, v171
	v_cmp_le_f32_e64 s[2:3], |v177|, v171
	v_cmp_le_f32_e64 s[10:11], |v178|, v171
	v_cmp_le_f32_e64 s[42:43], |v179|, v171
	v_cndmask_b32_e32 v204, v226, v204, vcc
	v_cndmask_b32_e64 v205, v226, v205, s[2:3]
	v_cndmask_b32_e64 v208, v226, v208, s[10:11]
	v_cndmask_b32_e64 v209, v226, v209, s[42:43]
	v_fma_f32 v176, s80, v220, v218
	v_fma_f32 v177, s81, v220, v218
	v_fma_f32 v212, v186, |v176|, v78
	v_fma_f32 v213, v186, |v177|, v79
	v_fma_f32 v216, v186, |v247|, v80
	v_fma_f32 v217, v186, |v245|, v81
	v_cmp_le_f32_e64 vcc, |v176|, v171
	v_cmp_le_f32_e64 s[2:3], |v177|, v171
	v_cmp_le_f32_e64 s[10:11], |v247|, v171
	v_cmp_le_f32_e64 s[42:43], |v245|, v171
	v_cndmask_b32_e32 v212, v226, v212, vcc
	v_cndmask_b32_e64 v213, v226, v213, s[2:3]
	v_cndmask_b32_e64 v216, v226, v216, s[10:11]
	v_cndmask_b32_e64 v217, v226, v217, s[42:43]
.LBB0_44:
	v_max3_f32 v51, v188, v189, v50
	v_max3_f32 v52, v190, v191, v169
	v_max3_f32 v51, v51, v194, v195
	v_max3_f32 v52, v52, v198, v199
	v_max3_f32 v51, v51, v192, v193
	v_max3_f32 v52, v52, v200, v201
	v_max3_f32 v51, v51, v196, v197
	v_max3_f32 v52, v52, v206, v207
	v_max3_f32 v51, v51, v202, v203
	v_max3_f32 v52, v52, v208, v209
	v_max3_f32 v51, v51, v204, v205
	v_max3_f32 v52, v52, v214, v215
	v_max3_f32 v51, v51, v210, v211
	v_max3_f32 v52, v52, v216, v217
	v_max3_f32 v51, v51, v212, v213
	v_max_f32_e32 v52, v52, v52
	v_max_f32_e32 v51, v51, v51
	v_max_f32_e32 v51, v51, v52
	v_cmp_lt_f32_e32 vcc, s90, v51
	s_cbranch_vccnz .LBB0_55
